# attention unit prologue: Q rows of the second query tile fetched by LDS-DMA with the first load batch (one dependent round trip fewer per unit)
# baseline (speedup 1.0000x reference)
.LBB0_396:
	s_barrier
	v_readlane_b32 s3, v254, 20
	v_readlane_b32 s2, v254, 4
	s_add_i32 s0, s3, 1
	s_lshr_b32 s2, s2, 3
	v_writelane_b32 v254, s0, 20
	s_lshr_b32 s0, s82, 3
	s_mul_i32 s3, s3, s0
	s_add_i32 s3, s3, s2
	v_mov_b32_e32 v0, s3
	s_movk_i32 s0, 0x7f
	s_waitcnt lgkmcnt(0)
	v_cmp_lt_i32_e32 vcc, s0, v0
	s_mov_b64 s[0:1], -1
	s_cbranch_vccnz .LBB0_395
	v_mov_b32_e32 v96, v193
	s_add_i32 s0, s3, s69
	s_bfe_u32 s2, s3, 0x10005
	v_readfirstlane_b32 s1, v96
	s_ashr_i32 s4, s0, 6
	s_and_b32 s72, s3, 31
	s_bfe_u32 s0, s1, 0x20006
	s_lshl_b32 s3, s2, 2
	s_add_i32 s0, s0, s3
	v_bfe_u32 v97, v96, 5, 1
	s_bfe_u32 s7, s1, 0x10008
	s_lshl_b32 s36, s0, 6
	s_lshl_b32 s1, s72, 7
	s_lshl_b32 s6, s7, 6
	s_ashr_i32 s37, s36, 31
	v_lshlrev_b32_e32 v40, 3, v97
	s_or_b32 s70, s6, s1
	s_lshl_b32 s71, s4, 12
	s_lshl_b64 s[36:37], s[36:37], 1
	v_cvt_f32_ubyte0_e32 v9, v40
	v_and_b32_e32 v222, 31, v96
	s_add_u32 s52, s28, s36
	v_cmp_lt_i32_e32 vcc, v208, v209
	v_mul_f32_e32 v10, 0xbf549a78, v9
	v_or_b32_e32 v80, s70, v222
	s_addc_u32 s53, s29, s37
	v_lshlrev_b32_e32 v198, 4, v97
	v_cndmask_b32_e32 v0, v207, v208, vcc
	v_cmp_gt_f32_e32 vcc, s30, v10
	v_lshl_add_u64 v[56:57], s[52:53], 0, v[198:199]
	v_lshlrev_b32_e32 v221, 2, v0
	v_or_b32_e32 v0, s71, v80
	v_cndmask_b32_e32 v10, 0, v213, vcc
	v_mad_i64_i32 v[0:1], s[52:53], v0, s25, v[56:57]
	v_and_b32_e32 v8, 32, v96
	v_fmac_f32_e32 v10, 0xbf549a78, v9
	s_lshl_b32 s98, s4, 8
	s_add_i32 s98, s98, 0x10000
	v_lshrrev_b32_e32 v238, 2, v193
	v_add_u32_e32 v238, s98, v238
	v_mov_b64_e32 v[240:241], s[28:29]
	v_mad_u64_u32 v[240:241], s[100:101], v238, s25, v[240:241]
	s_lshl_b32 s98, s2, 7
	s_mov_b32 s99, 0
	v_lshl_add_u64 v[240:241], v[240:241], 0, s[98:99]
	v_bfe_u32 v242, v193, 1, 1
	v_mov_b32_e32 v243, 0
	v_lshlrev_b32_e32 v242, 6, v242
	v_lshl_add_u64 v[244:245], v[240:241], 0, v[242:243]
	v_and_b32_e32 v242, 1, v193
	v_lshlrev_b32_e32 v242, 4, v242
	v_lshl_add_u64 v[244:245], v[244:245], 0, v[242:243]
	v_and_b32_e32 v242, 3, v193
	v_lshlrev_b32_e32 v242, 5, v242
	v_lshl_add_u64 v[246:247], v[240:241], 0, v[242:243]
	global_load_dwordx4 v[176:179], v[244:245], off offset:1024
	global_load_dwordx4 v[180:183], v[244:245], off offset:1056
	global_load_dwordx4 v[184:187], v[246:247], off offset:1296
	global_load_dwordx4 v[188:191], v[246:247], off offset:1280
	global_load_dwordx4 v[24:27], v[0:1], off
	global_load_dwordx4 v[28:31], v[0:1], off offset:32
	global_load_dwordx4 v[88:91], v[0:1], off offset:64
	global_load_dwordx4 v[92:95], v[0:1], off offset:96
	global_load_dwordx4 v[16:19], v8, s[14:15]
	global_load_dwordx4 v[20:23], v8, s[14:15] offset:16
	global_load_dwordx4 v[4:7], v8, s[14:15] offset:64
	s_nop 0
	global_load_dwordx4 v[0:3], v8, s[14:15] offset:80
	global_load_dwordx4 v[100:103], v8, s[14:15] offset:128
	global_load_dwordx4 v[52:55], v8, s[14:15] offset:144
	v_exp_f32_e32 v32, v10
	global_load_dwordx4 v[12:15], v8, s[14:15] offset:192
	s_nop 0
	global_load_dwordx4 v[8:11], v8, s[14:15] offset:208
	v_or_b32_e32 v248, 32, v80
	v_or_b32_e32 v248, s71, v248
	v_mad_i64_i32 v[250:251], s[52:53], v248, s25, v[56:57]
	v_readfirstlane_b32 s98, v195
	s_lshl_b32 s98, s98, 12
	s_add_i32 s98, s98, 0xa000
	v_lshl_add_u32 v252, v192, 4, s98
	s_mov_b32 m0, s98
	s_nop 0
	global_load_lds_dwordx4 v[250:251], off
	s_add_i32 m0, s98, 0x3e0
	s_nop 0
	global_load_lds_dwordx4 v[250:251], off offset:32
	s_add_i32 m0, s98, 0x7c0
	s_nop 0
	global_load_lds_dwordx4 v[250:251], off offset:64
	s_add_i32 m0, s98, 0xba0
	s_nop 0
	global_load_lds_dwordx4 v[250:251], off offset:96
	v_cndmask_b32_e32 v33, 0, v214, vcc
	s_lshr_b32 s1, s70, 6
	v_ldexp_f32 v81, v32, v33
	v_or_b32_e32 v33, 1, v40
	v_cvt_f32_ubyte0_e32 v33, v33
	v_mul_f32_e32 v34, 0xbf549a78, v33
	v_cmp_gt_f32_e32 vcc, s30, v34
	v_cvt_f32_ubyte0_e32 v41, s1
	v_mul_f32_e32 v32, v81, v41
	v_cndmask_b32_e32 v34, 0, v213, vcc
	v_fmac_f32_e32 v34, 0xbf549a78, v33
	v_cvt_f32_ubyte0_e32 v50, v222
	v_mul_f32_e32 v32, 0.15915494, v32
	v_exp_f32_e32 v33, v34
	v_sin_f32_e32 v42, v32
	v_cos_f32_e32 v43, v32
	v_mul_f32_e32 v32, v81, v50
	v_mul_f32_e32 v32, 0.15915494, v32
	v_sin_f32_e32 v62, v32
	v_cos_f32_e32 v63, v32
	v_cndmask_b32_e32 v32, 0, v214, vcc
	v_ldexp_f32 v82, v33, v32
	v_or_b32_e32 v33, 2, v40
	v_cvt_f32_ubyte0_e32 v33, v33
	v_mul_f32_e32 v34, 0xbf549a78, v33
	v_cmp_gt_f32_e32 vcc, s30, v34
	v_mul_f32_e32 v32, v82, v41
	v_mul_f32_e32 v32, 0.15915494, v32
	v_cndmask_b32_e32 v34, 0, v213, vcc
	v_fmac_f32_e32 v34, 0xbf549a78, v33
	v_exp_f32_e32 v33, v34
	v_sin_f32_e32 v45, v32
	v_cos_f32_e32 v44, v32
	v_mul_f32_e32 v32, v82, v50
	v_mul_f32_e32 v32, 0.15915494, v32
	v_sin_f32_e32 v65, v32
	v_cos_f32_e32 v64, v32
	v_cndmask_b32_e32 v32, 0, v214, vcc
	v_ldexp_f32 v83, v33, v32
	v_or_b32_e32 v33, 3, v40
	v_cvt_f32_ubyte0_e32 v33, v33
	v_mul_f32_e32 v34, 0xbf549a78, v33
	v_mul_f32_e32 v32, v83, v41
	v_cmp_gt_f32_e32 vcc, s30, v34
	v_mul_f32_e32 v32, 0.15915494, v32
	v_or_b32_e32 v35, 4, v40
	v_cndmask_b32_e32 v34, 0, v213, vcc
	v_sin_f32_e32 v46, v32
	v_cos_f32_e32 v47, v32
	v_mul_f32_e32 v32, v83, v50
	v_fmac_f32_e32 v34, 0xbf549a78, v33
	v_cvt_f32_ubyte0_e32 v35, v35
	v_mul_f32_e32 v32, 0.15915494, v32
	v_exp_f32_e32 v33, v34
	v_mul_f32_e32 v36, 0xbf549a78, v35
	v_sin_f32_e32 v70, v32
	v_cos_f32_e32 v71, v32
	v_cndmask_b32_e32 v32, 0, v214, vcc
	v_cmp_gt_f32_e32 vcc, s30, v36
	v_ldexp_f32 v84, v33, v32
	v_or_b32_e32 v37, 5, v40
	v_cndmask_b32_e32 v36, 0, v213, vcc
	v_fmac_f32_e32 v36, 0xbf549a78, v35
	v_exp_f32_e32 v35, v36
	v_mul_f32_e32 v34, v84, v50
	v_cvt_f32_ubyte0_e32 v37, v37
	v_mul_f32_e32 v34, 0.15915494, v34
	v_mul_f32_e32 v38, 0xbf549a78, v37
	v_sin_f32_e32 v73, v34
	v_cos_f32_e32 v72, v34
	v_cndmask_b32_e32 v34, 0, v214, vcc
	v_cmp_gt_f32_e32 vcc, s30, v38
	v_ldexp_f32 v85, v35, v34
	v_or_b32_e32 v39, 6, v40
	v_cndmask_b32_e32 v38, 0, v213, vcc
	v_mul_f32_e32 v36, v85, v50
	v_fmac_f32_e32 v38, 0xbf549a78, v37
	v_cvt_f32_ubyte0_e32 v39, v39
	v_mul_f32_e32 v36, 0.15915494, v36
	v_exp_f32_e32 v37, v38
	v_mul_f32_e32 v48, 0xbf549a78, v39
	v_sin_f32_e32 v74, v36
	v_cos_f32_e32 v75, v36
	v_cndmask_b32_e32 v36, 0, v214, vcc
	v_cmp_gt_f32_e32 vcc, s30, v48
	v_ldexp_f32 v86, v37, v36
	v_mul_f32_e32 v38, v86, v50
	v_cndmask_b32_e32 v48, 0, v213, vcc
	v_fmac_f32_e32 v48, 0xbf549a78, v39
	v_exp_f32_e32 v39, v48
	v_mul_f32_e32 v38, 0.15915494, v38
	v_sin_f32_e32 v77, v38
	v_cos_f32_e32 v76, v38
	v_cndmask_b32_e32 v38, 0, v214, vcc
	v_ldexp_f32 v87, v39, v38
	v_mul_f32_e32 v48, v87, v50
	v_or_b32_e32 v40, 7, v40
	v_mul_f32_e32 v48, 0.15915494, v48
	v_cvt_f32_ubyte0_e32 v40, v40
	v_sin_f32_e32 v66, v48
	v_cos_f32_e32 v67, v48
	v_mul_f32_e32 v48, 0xbf549a78, v40
	v_cmp_gt_f32_e32 vcc, s30, v48
	s_waitcnt vmcnt(0)
	v_mov_b32_e32 v49, v10
	v_lshlrev_b32_e32 v60, 16, v91
	v_cndmask_b32_e32 v48, 0, v213, vcc
	v_fmac_f32_e32 v48, 0xbf549a78, v40
	v_exp_f32_e32 v40, v48
	v_cndmask_b32_e32 v10, 0, v214, vcc
	v_and_b32_e32 v104, 0xffff0000, v91
	v_mul_f32_e32 v32, v84, v41
	v_ldexp_f32 v99, v40, v10
	v_mul_f32_e32 v10, v99, v41
	v_mul_f32_e32 v10, 0.15915494, v10
	v_mul_f32_e32 v34, v85, v41
	v_mul_f32_e32 v36, v86, v41
	v_mul_f32_e32 v38, v87, v41
	v_lshlrev_b32_e32 v61, 16, v95
	v_sin_f32_e32 v41, v10
	v_cos_f32_e32 v40, v10
	v_mul_f32_e32 v10, v99, v50
	v_and_b32_e32 v105, 0xffff0000, v95
	v_mov_b32_e32 v50, v104
	v_mov_b32_e32 v51, v60
	v_pk_mul_f32 v[106:107], v[50:51], v[50:51]
	v_mov_b32_e32 v50, v105
	v_mov_b32_e32 v51, v61
	v_pk_mul_f32 v[108:109], v[50:51], v[50:51]
	v_mov_b32_e32 v51, v8
	v_mov_b32_e32 v8, v53
	v_lshlrev_b32_e32 v112, 16, v89
	v_mov_b32_e32 v53, v14
	v_and_b32_e32 v114, 0xffff0000, v89
	v_mov_b32_e32 v14, v103
	v_lshlrev_b32_e32 v103, 16, v92
	v_and_b32_e32 v89, 0xffff0000, v92
	v_lshlrev_b32_e32 v140, 16, v25
	v_and_b32_e32 v144, 0xffff0000, v25
	v_lshlrev_b32_e32 v149, 16, v28
	v_lshlrev_b32_e32 v148, 16, v24
	v_and_b32_e32 v25, 0xffff0000, v28
	v_and_b32_e32 v24, 0xffff0000, v24
	v_mov_b32_e32 v58, v89
	v_mov_b32_e32 v59, v103
	v_lshlrev_b32_e32 v141, 16, v29
	v_and_b32_e32 v145, 0xffff0000, v29
	v_pk_mul_f32 v[150:151], v[148:149], v[148:149]
	v_pk_mul_f32 v[28:29], v[24:25], v[24:25]
	v_lshlrev_b32_e32 v113, 16, v93
	v_and_b32_e32 v115, 0xffff0000, v93
	v_pk_mul_f32 v[92:93], v[58:59], v[58:59]
	v_mov_b32_e32 v58, v22
	v_mov_b32_e32 v22, v20
	v_pk_mul_f32 v[142:143], v[140:141], v[140:141]
	v_add_f32_e32 v20, v150, v28
	v_lshlrev_b32_e32 v137, 16, v30
	v_lshlrev_b32_e32 v136, 16, v26
	v_pk_mul_f32 v[146:147], v[144:145], v[144:145]
	v_add_f32_e32 v20, v142, v20
	v_lshlrev_b32_e32 v128, 16, v27
	v_and_b32_e32 v132, 0xffff0000, v27
	v_pk_mul_f32 v[138:139], v[136:137], v[136:137]
	v_and_b32_e32 v27, 0xffff0000, v30
	v_and_b32_e32 v26, 0xffff0000, v26
	v_add_f32_e32 v20, v146, v20
	v_lshlrev_b32_e32 v129, 16, v31
	v_and_b32_e32 v133, 0xffff0000, v31
	v_pk_mul_f32 v[30:31], v[26:27], v[26:27]
	v_add_f32_e32 v20, v138, v20
	v_pk_mul_f32 v[130:131], v[128:129], v[128:129]
	v_add_f32_e32 v20, v30, v20
	v_pk_mul_f32 v[134:135], v[132:133], v[132:133]
	v_add_f32_e32 v20, v130, v20
	v_add_f32_e32 v20, v134, v20
	v_add_f32_e32 v20, v151, v20
	v_add_f32_e32 v20, v29, v20
	v_add_f32_e32 v20, v143, v20
	v_add_f32_e32 v20, v147, v20
	v_add_f32_e32 v20, v139, v20
	v_add_f32_e32 v20, v31, v20
	v_add_f32_e32 v20, v131, v20
	v_mov_b32_e32 v50, v52
	v_mov_b32_e32 v52, v102
	v_lshlrev_b32_e32 v102, 16, v88
	v_add_f32_e32 v20, v135, v20
	v_and_b32_e32 v88, 0xffff0000, v88
	v_fmac_f32_e32 v20, v102, v102
	v_fmac_f32_e32 v20, v88, v88
	v_fmac_f32_e32 v20, v112, v112
	v_lshlrev_b32_e32 v110, 16, v90
	v_fmac_f32_e32 v20, v114, v114
	v_and_b32_e32 v90, 0xffff0000, v90
	v_fmac_f32_e32 v20, v110, v110
	v_fmac_f32_e32 v20, v90, v90
	v_mul_f32_e32 v10, 0.15915494, v10
	v_lshlrev_b32_e32 v111, 16, v94
	v_and_b32_e32 v91, 0xffff0000, v94
	v_add_f32_e32 v20, v107, v20
	v_mov_b32_e32 v48, v54
	v_sin_f32_e32 v69, v10
	v_cos_f32_e32 v68, v10
	v_mov_b32_e32 v10, v55
	v_mov_b32_e32 v54, v91
	v_mov_b32_e32 v55, v111
	v_add_f32_e32 v20, v106, v20
	v_pk_mul_f32 v[94:95], v[54:55], v[54:55]
	v_mov_b32_e32 v54, v115
	v_mov_b32_e32 v55, v113
	v_add_f32_e32 v20, v93, v20
	v_pk_mul_f32 v[116:117], v[54:55], v[54:55]
	v_add_f32_e32 v20, v92, v20
	v_add_f32_e32 v20, v117, v20
	v_add_f32_e32 v20, v116, v20
	v_add_f32_e32 v20, v95, v20
	v_add_f32_e32 v20, v94, v20
	v_add_f32_e32 v20, v109, v20
	v_add_f32_e32 v20, v108, v20
	ds_bpermute_b32 v30, v221, v20
	v_mov_b32_e32 v29, v6
	v_mov_b32_e32 v28, v18
	v_mov_b32_e32 v31, v4
	v_mov_b32_e32 v54, v100
	s_waitcnt lgkmcnt(0)
	v_add_f32_e32 v6, v20, v30
	v_fmamk_f32 v6, v6, 0x3c800000, v211
	v_mul_f32_e32 v18, 0x4b800000, v6
	v_cmp_gt_f32_e32 vcc, s33, v6
	v_mov_b32_e32 v55, v12
	v_mov_b32_e32 v30, v16
	v_cndmask_b32_e32 v6, v6, v18, vcc
	v_rsq_f32_e32 v18, v6
	v_mov_b32_e32 v12, v101
	v_mov_b32_e32 v59, v2
	v_mov_b32_e32 v2, v23
	v_mul_f32_e32 v4, 0x45800000, v18
	v_cndmask_b32_e32 v16, v18, v4, vcc
	v_pk_mul_f32 v[116:117], v[54:55], v[16:17] op_sel_hi:[1,0]
	v_mov_b32_e32 v23, v0
	v_pk_mul_f32 v[102:103], v[116:117], v[102:103]
	v_pk_mul_f32 v[116:117], v[12:13], v[16:17] op_sel_hi:[1,0]
	v_mov_b32_e32 v0, v21
	v_pk_mul_f32 v[88:89], v[116:117], v[88:89]
	v_pk_mul_f32 v[116:117], v[52:53], v[16:17] op_sel_hi:[1,0]
	v_mov_b32_e32 v4, v17
	v_pk_mul_f32 v[112:113], v[116:117], v[112:113]
	v_pk_mul_f32 v[116:117], v[14:15], v[16:17] op_sel_hi:[1,0]
	v_mov_b32_e32 v6, v19
	v_pk_mul_f32 v[114:115], v[116:117], v[114:115]
	v_pk_mul_f32 v[116:117], v[50:51], v[16:17] op_sel_hi:[1,0]
	v_pk_mul_f32 v[18:19], v[30:31], v[16:17] op_sel_hi:[1,0]
	v_pk_mul_f32 v[110:111], v[116:117], v[110:111]
	v_pk_mul_f32 v[116:117], v[8:9], v[16:17] op_sel_hi:[1,0]
	v_pk_mul_f32 v[20:21], v[4:5], v[16:17] op_sel_hi:[1,0]
	v_pk_mul_f32 v[106:107], v[0:1], v[16:17] op_sel_hi:[1,0]
	v_pk_mul_f32 v[90:91], v[116:117], v[90:91]
	v_pk_mul_f32 v[116:117], v[48:49], v[16:17] op_sel_hi:[1,0]
	v_pk_mul_f32 v[18:19], v[18:19], v[148:149]
	v_pk_mul_f32 v[20:21], v[20:21], v[24:25]
	v_pk_mul_f32 v[24:25], v[28:29], v[16:17] op_sel_hi:[1,0]
	v_pk_mul_f32 v[92:93], v[6:7], v[16:17] op_sel_hi:[1,0]
	v_pk_mul_f32 v[94:95], v[22:23], v[16:17] op_sel_hi:[1,0]
	v_pk_mul_f32 v[26:27], v[106:107], v[26:27]
	v_pk_mul_f32 v[106:107], v[58:59], v[16:17] op_sel_hi:[1,0]
	v_pk_mul_f32 v[108:109], v[2:3], v[16:17] op_sel_hi:[1,0]
	v_pk_mul_f32 v[116:117], v[116:117], v[60:61]
	v_pk_mul_f32 v[16:17], v[10:11], v[16:17] op_sel_hi:[1,0]
	v_mov_b32_e32 v60, v43
	v_mov_b32_e32 v61, v42
	v_pk_mul_f32 v[104:105], v[16:17], v[104:105]
	v_pk_mul_f32 v[16:17], v[60:61], v[18:19]
	v_pk_mul_f32 v[106:107], v[106:107], v[128:129]
	v_sub_f32_e32 v16, v16, v17
	v_mul_f32_e32 v128, 0x3e38aa3b, v16
	v_pk_mul_f32 v[16:17], v[42:43], v[18:19]
	v_mov_b32_e32 v100, v63
	v_mov_b32_e32 v101, v62
	v_add_f32_e32 v16, v16, v17
	v_pk_mul_f32 v[108:109], v[108:109], v[132:133]
	v_mul_f32_e32 v132, 0x3e38aa3b, v16
	v_pk_mul_f32 v[16:17], v[100:101], v[102:103]
	v_pk_mul_f32 v[24:25], v[24:25], v[140:141]
	v_sub_f32_e32 v16, v16, v17
	v_mul_f32_e32 v100, 0x3e38aa3b, v16
	v_pk_mul_f32 v[16:17], v[62:63], v[102:103]
	v_mov_b32_e32 v62, v45
	v_add_f32_e32 v16, v16, v17
	v_mul_f32_e32 v140, 0x3e38aa3b, v16
	v_pk_mul_f32 v[16:17], v[44:45], v[20:21]
	v_mov_b32_e32 v63, v44
	v_sub_f32_e32 v16, v16, v17
	v_mul_f32_e32 v101, 0x3e38aa3b, v16
	v_pk_mul_f32 v[16:17], v[62:63], v[20:21]
	v_mov_b32_e32 v118, v65
	v_add_f32_e32 v16, v16, v17
	v_mul_f32_e32 v102, 0x3e38aa3b, v16
	v_pk_mul_f32 v[16:17], v[64:65], v[88:89]
	v_mov_b32_e32 v119, v64
	v_sub_f32_e32 v16, v16, v17
	v_mul_f32_e32 v103, 0x3e38aa3b, v16
	v_pk_mul_f32 v[16:17], v[118:119], v[88:89]
	v_mov_b32_e32 v64, v47
	v_add_f32_e32 v16, v16, v17
	v_mov_b32_e32 v65, v46
	v_mul_f32_e32 v118, 0x3e38aa3b, v16
	v_pk_mul_f32 v[16:17], v[64:65], v[24:25]
	v_mul_f32_e32 v32, 0.15915494, v32
	v_sub_f32_e32 v16, v16, v17
	v_mul_f32_e32 v119, 0x3e38aa3b, v16
	v_pk_mul_f32 v[16:17], v[46:47], v[24:25]
	v_mov_b32_e32 v120, v71
	v_mov_b32_e32 v121, v70
	v_add_f32_e32 v16, v16, v17
	v_sin_f32_e32 v33, v32
	v_cos_f32_e32 v32, v32
	v_mul_f32_e32 v133, 0x3e38aa3b, v16
	v_pk_mul_f32 v[16:17], v[120:121], v[112:113]
	v_pk_mul_f32 v[92:93], v[92:93], v[144:145]
	v_sub_f32_e32 v16, v16, v17
	v_mul_f32_e32 v120, 0x3e38aa3b, v16
	v_pk_mul_f32 v[16:17], v[70:71], v[112:113]
	v_mul_f32_e32 v35, 0.15915494, v34
	v_add_f32_e32 v16, v16, v17
	v_mul_f32_e32 v70, 0x3e38aa3b, v16
	v_pk_mul_f32 v[16:17], v[32:33], v[92:93]
	v_sin_f32_e32 v34, v35
	v_sub_f32_e32 v16, v16, v17
	v_mul_f32_e32 v71, 0x3e38aa3b, v16
	v_mov_b32_e32 v16, v33
	v_mov_b32_e32 v17, v32
	v_pk_mul_f32 v[18:19], v[16:17], v[92:93]
	v_cos_f32_e32 v35, v35
	v_add_f32_e32 v18, v18, v19
	v_mul_f32_e32 v112, 0x3e38aa3b, v18
	v_pk_mul_f32 v[18:19], v[72:73], v[114:115]
	v_mov_b32_e32 v122, v73
	v_mov_b32_e32 v123, v72
	v_sub_f32_e32 v18, v18, v19
	v_mul_f32_e32 v72, 0x3e38aa3b, v18
	v_pk_mul_f32 v[18:19], v[122:123], v[114:115]
	v_pk_mul_f32 v[94:95], v[94:95], v[136:137]
	v_add_f32_e32 v18, v18, v19
	v_mul_f32_e32 v73, 0x3e38aa3b, v18
	v_mov_b32_e32 v18, v35
	v_mov_b32_e32 v19, v34
	v_pk_mul_f32 v[20:21], v[18:19], v[94:95]
	v_mul_f32_e32 v36, 0.15915494, v36
	v_sub_f32_e32 v20, v20, v21
	v_mul_f32_e32 v113, 0x3e38aa3b, v20
	v_pk_mul_f32 v[20:21], v[34:35], v[94:95]
	v_mov_b32_e32 v124, v75
	v_mov_b32_e32 v125, v74
	v_add_f32_e32 v20, v20, v21
	v_sin_f32_e32 v37, v36
	v_cos_f32_e32 v36, v36
	v_mul_f32_e32 v114, 0x3e38aa3b, v20
	v_pk_mul_f32 v[20:21], v[124:125], v[110:111]
	v_mul_f32_e32 v39, 0.15915494, v38
	v_sub_f32_e32 v20, v20, v21
	v_mul_f32_e32 v115, 0x3e38aa3b, v20
	v_pk_mul_f32 v[20:21], v[74:75], v[110:111]
	v_sin_f32_e32 v38, v39
	v_add_f32_e32 v20, v20, v21
	v_mul_f32_e32 v74, 0x3e38aa3b, v20
	v_pk_mul_f32 v[20:21], v[36:37], v[26:27]
	v_cos_f32_e32 v39, v39
	v_sub_f32_e32 v20, v20, v21
	v_mul_f32_e32 v75, 0x3e38aa3b, v20
	v_mov_b32_e32 v20, v37
	v_mov_b32_e32 v21, v36
	v_pk_mul_f32 v[24:25], v[20:21], v[26:27]
	v_mov_b32_e32 v126, v77
	v_add_f32_e32 v24, v24, v25
	v_mul_f32_e32 v110, 0x3e38aa3b, v24
	v_pk_mul_f32 v[24:25], v[76:77], v[90:91]
	v_mov_b32_e32 v127, v76
	v_sub_f32_e32 v24, v24, v25
	v_mul_f32_e32 v76, 0x3e38aa3b, v24
	v_pk_mul_f32 v[24:25], v[126:127], v[90:91]
	v_mov_b32_e32 v78, v67
	v_add_f32_e32 v24, v24, v25
	v_or_b32_e32 v25, 32, v80
	v_or_b32_e32 v25, s71, v25
	v_mad_i64_i32 v[56:57], s[52:53], v25, s25, v[56:57]
	v_mul_f32_e32 v77, 0x3e38aa3b, v24
	v_mov_b32_e32 v24, v39
	v_mov_b32_e32 v25, v38
	v_pk_mul_f32 v[26:27], v[24:25], v[106:107]
	v_mov_b32_e32 v79, v66
	v_sub_f32_e32 v26, v26, v27
	v_mul_f32_e32 v111, 0x3e38aa3b, v26
	v_pk_mul_f32 v[26:27], v[38:39], v[106:107]
	ds_read_b128 v[88:91], v252 offset:2048
	ds_read_b128 v[92:95], v252 offset:3072
	v_add_f32_e32 v26, v26, v27
	v_mul_f32_e32 v106, 0x3e38aa3b, v26
	v_pk_mul_f32 v[26:27], v[78:79], v[116:117]
	v_cvt_pk_bf16_f32 v128, v128, v101
	v_cvt_pk_bf16_f32 v132, v132, v102
	v_cvt_pk_bf16_f32 v136, v100, v103
	v_cvt_pk_bf16_f32 v130, v113, v75
	v_cvt_pk_bf16_f32 v142, v74, v77
	s_nop 0
	v_sub_f32_e32 v26, v26, v27
	v_mul_f32_e32 v78, 0x3e38aa3b, v26
	v_pk_mul_f32 v[26:27], v[66:67], v[116:117]
	v_cvt_pk_bf16_f32 v137, v120, v72
	v_cvt_pk_bf16_f32 v141, v70, v73
	v_cvt_pk_bf16_f32 v129, v119, v71
	v_cvt_pk_bf16_f32 v138, v115, v76
	v_cvt_pk_bf16_f32 v134, v114, v110
	s_nop 0
	v_add_f32_e32 v26, v26, v27
	v_mul_f32_e32 v79, 0x3e38aa3b, v26
	v_pk_mul_f32 v[26:27], v[40:41], v[108:109]
	v_cvt_pk_bf16_f32 v140, v140, v118
	v_cvt_pk_bf16_f32 v133, v133, v112
	v_and_b32_e32 v98, 63, v96
	v_sub_f32_e32 v26, v26, v27
	v_mul_f32_e32 v107, 0x3e38aa3b, v26
	v_mov_b32_e32 v26, v41
	v_mov_b32_e32 v27, v40
	v_pk_mul_f32 v[66:67], v[26:27], v[108:109]
	v_cvt_pk_bf16_f32 v131, v111, v107
	s_ashr_i32 s1, s0, 31
	v_add_f32_e32 v66, v66, v67
	v_mul_f32_e32 v108, 0x3e38aa3b, v66
	v_pk_mul_f32 v[66:67], v[68:69], v[104:105]
	v_cvt_pk_bf16_f32 v135, v106, v108
	s_lshl_b64 s[0:1], s[0:1], 2
	v_sub_f32_e32 v66, v66, v67
	v_mul_f32_e32 v109, 0x3e38aa3b, v66
	v_mov_b32_e32 v66, v69
	v_mov_b32_e32 v67, v68
	v_pk_mul_f32 v[66:67], v[66:67], v[104:105]
	ds_read_b128 v[100:103], v252
	ds_read_b128 v[104:107], v252 offset:1024
	v_bitop3_b32 v56, v80, 63, 32 bitop3:0xc8
	v_cvt_f32_ubyte0_e32 v56, v56
	v_mul_f32_e32 v57, v81, v56
	v_mul_f32_e32 v57, 0.15915494, v57
	v_sin_f32_e32 v80, v57
	v_cos_f32_e32 v81, v57
	v_mul_f32_e32 v57, v82, v56
	v_mul_f32_e32 v57, 0.15915494, v57
	v_cvt_pk_bf16_f32 v139, v78, v109
	v_sin_f32_e32 v109, v57
	v_cos_f32_e32 v108, v57
	v_mul_f32_e32 v57, v83, v56
	v_mul_f32_e32 v57, 0.15915494, v57
	v_sin_f32_e32 v74, v57
	v_cos_f32_e32 v75, v57
	v_mul_f32_e32 v57, v84, v56
	v_mul_f32_e32 v57, 0.15915494, v57
	v_sin_f32_e32 v73, v57
	v_cos_f32_e32 v72, v57
	v_mul_f32_e32 v57, v85, v56
	v_mul_f32_e32 v57, 0.15915494, v57
	v_sin_f32_e32 v70, v57
	v_cos_f32_e32 v71, v57
	v_mul_f32_e32 v57, v86, v56
	v_mul_f32_e32 v57, 0.15915494, v57
	v_sin_f32_e32 v69, v57
	v_cos_f32_e32 v68, v57
	v_mul_f32_e32 v57, v87, v56
	v_mul_f32_e32 v56, v99, v56
	v_mov_b32_e32 v122, v81
	v_mov_b32_e32 v123, v80
	v_mov_b32_e32 v124, v109
	v_mov_b32_e32 v125, v108
	v_add_f32_e32 v66, v66, v67
	v_mul_f32_e32 v66, 0x3e38aa3b, v66
	v_cvt_pk_bf16_f32 v143, v79, v66
	v_mov_b32_e32 v78, v75
	v_mov_b32_e32 v79, v74
	s_waitcnt lgkmcnt(0)
	v_lshlrev_b32_e32 v82, 16, v91
	v_and_b32_e32 v84, 0xffff0000, v91
	s_waitcnt lgkmcnt(0)
	v_lshlrev_b32_e32 v83, 16, v95
	v_and_b32_e32 v85, 0xffff0000, v95
	v_mov_b32_e32 v76, v84
	v_mov_b32_e32 v77, v82
	v_pk_mul_f32 v[86:87], v[76:77], v[76:77]
	v_mov_b32_e32 v76, v85
	v_mov_b32_e32 v77, v83
	v_lshlrev_b32_e32 v113, 16, v94
	v_and_b32_e32 v91, 0xffff0000, v94
	v_pk_mul_f32 v[110:111], v[76:77], v[76:77]
	v_mov_b32_e32 v76, v91
	v_mov_b32_e32 v77, v113
	v_lshlrev_b32_e32 v115, 16, v93
	v_and_b32_e32 v117, 0xffff0000, v93
	v_pk_mul_f32 v[94:95], v[76:77], v[76:77]
	v_lshlrev_b32_e32 v114, 16, v89
	v_and_b32_e32 v116, 0xffff0000, v89
	v_mov_b32_e32 v76, v117
	v_mov_b32_e32 v77, v115
	v_lshlrev_b32_e32 v121, 16, v92
	v_and_b32_e32 v89, 0xffff0000, v92
	v_pk_mul_f32 v[118:119], v[76:77], v[76:77]
	v_mov_b32_e32 v76, v89
	v_mov_b32_e32 v77, v121
	v_pk_mul_f32 v[92:93], v[76:77], v[76:77]
	v_lshlrev_b32_e32 v120, 16, v88
	v_and_b32_e32 v88, 0xffff0000, v88
	v_lshlrev_b32_e32 v112, 16, v90
	v_and_b32_e32 v90, 0xffff0000, v90
	v_mov_b32_e32 v76, v73
	v_mul_f32_e32 v57, 0.15915494, v57
	v_sin_f32_e32 v66, v57
	v_cos_f32_e32 v67, v57
	s_add_u32 s0, s18, s0
	s_addc_u32 s1, s19, s1
	v_mul_f32_e32 v56, 0.15915494, v56
	v_sin_f32_e32 v57, v56
	v_cos_f32_e32 v56, v56
	s_waitcnt lgkmcnt(0)
	v_lshlrev_b32_e32 v154, 16, v101
	v_and_b32_e32 v158, 0xffff0000, v101
	s_waitcnt lgkmcnt(0)
	v_lshlrev_b32_e32 v163, 16, v104
	v_lshlrev_b32_e32 v162, 16, v100
	v_and_b32_e32 v101, 0xffff0000, v104
	v_and_b32_e32 v100, 0xffff0000, v100
	v_lshlrev_b32_e32 v155, 16, v105
	v_and_b32_e32 v159, 0xffff0000, v105
	v_pk_mul_f32 v[164:165], v[162:163], v[162:163]
	v_pk_mul_f32 v[104:105], v[100:101], v[100:101]
	v_pk_mul_f32 v[156:157], v[154:155], v[154:155]
	v_add_f32_e32 v77, v164, v104
	v_lshlrev_b32_e32 v151, 16, v106
	v_lshlrev_b32_e32 v150, 16, v102
	v_pk_mul_f32 v[160:161], v[158:159], v[158:159]
	v_add_f32_e32 v77, v156, v77
	v_lshlrev_b32_e32 v126, 16, v103
	v_and_b32_e32 v146, 0xffff0000, v103
	v_pk_mul_f32 v[152:153], v[150:151], v[150:151]
	v_and_b32_e32 v103, 0xffff0000, v106
	v_and_b32_e32 v102, 0xffff0000, v102
	v_add_f32_e32 v77, v160, v77
	v_lshlrev_b32_e32 v127, 16, v107
	v_and_b32_e32 v147, 0xffff0000, v107
	v_pk_mul_f32 v[106:107], v[102:103], v[102:103]
	v_add_f32_e32 v77, v152, v77
	v_pk_mul_f32 v[144:145], v[126:127], v[126:127]
	v_add_f32_e32 v77, v106, v77
	v_pk_mul_f32 v[148:149], v[146:147], v[146:147]
	v_add_f32_e32 v77, v144, v77
	v_add_f32_e32 v77, v148, v77
	v_add_f32_e32 v77, v165, v77
	v_add_f32_e32 v77, v105, v77
	v_add_f32_e32 v77, v157, v77
	v_add_f32_e32 v77, v161, v77
	v_add_f32_e32 v77, v153, v77
	v_add_f32_e32 v77, v107, v77
	v_add_f32_e32 v77, v145, v77
	v_add_f32_e32 v77, v149, v77
	v_fmac_f32_e32 v77, v120, v120
	v_fmac_f32_e32 v77, v88, v88
	v_fmac_f32_e32 v77, v114, v114
	v_fmac_f32_e32 v77, v116, v116
	v_fmac_f32_e32 v77, v112, v112
	v_fmac_f32_e32 v77, v90, v90
	v_add_f32_e32 v77, v87, v77
	v_add_f32_e32 v77, v86, v77
	v_add_f32_e32 v77, v93, v77
	v_add_f32_e32 v77, v92, v77
	v_add_f32_e32 v77, v119, v77
	v_add_f32_e32 v77, v118, v77
	v_add_f32_e32 v77, v95, v77
	v_add_f32_e32 v77, v94, v77
	v_add_f32_e32 v77, v111, v77
	v_add_f32_e32 v93, v110, v77
	ds_bpermute_b32 v94, v221, v93
	v_mov_b32_e32 v77, v72
	v_mov_b32_e32 v86, v71
	v_mov_b32_e32 v87, v70
	v_mov_b32_e32 v92, v69
	s_waitcnt lgkmcnt(0)
	v_add_f32_e32 v93, v93, v94
	v_fmamk_f32 v93, v93, 0x3c800000, v211
	v_mul_f32_e32 v94, 0x4b800000, v93
	v_cmp_gt_f32_e32 vcc, s33, v93
	v_mov_b32_e32 v95, v66
	s_lshl_b32 s52, s4, 8
	v_cndmask_b32_e32 v93, v93, v94, vcc
	v_rsq_f32_e32 v99, v93
	v_mov_b32_e32 v93, v68
	v_mov_b32_e32 v94, v67
	s_ashr_i32 s53, s52, 31
	v_mul_f32_e32 v104, 0x45800000, v99
	v_cndmask_b32_e32 v104, v99, v104, vcc
	v_pk_mul_f32 v[30:31], v[30:31], v[104:105] op_sel_hi:[1,0]
	v_pk_mul_f32 v[54:55], v[54:55], v[104:105] op_sel_hi:[1,0]
	v_pk_mul_f32 v[30:31], v[30:31], v[162:163]
	v_pk_mul_f32 v[54:55], v[54:55], v[120:121]
	v_pk_mul_f32 v[60:61], v[60:61], v[30:31]
	v_pk_mul_f32 v[30:31], v[42:43], v[30:31]
	v_pk_mul_f32 v[4:5], v[4:5], v[104:105] op_sel_hi:[1,0]
	v_add_f32_e32 v30, v30, v31
	v_mul_f32_e32 v42, 0x3e38aa3b, v30
	v_pk_mul_f32 v[30:31], v[122:123], v[54:55]
	v_pk_mul_f32 v[4:5], v[4:5], v[100:101]
	v_sub_f32_e32 v30, v30, v31
	v_mul_f32_e32 v43, 0x3e38aa3b, v30
	v_pk_mul_f32 v[30:31], v[80:81], v[54:55]
	v_pk_mul_f32 v[12:13], v[12:13], v[104:105] op_sel_hi:[1,0]
	v_add_f32_e32 v30, v30, v31
	v_mul_f32_e32 v54, 0x3e38aa3b, v30
	v_pk_mul_f32 v[30:31], v[44:45], v[4:5]
	v_pk_mul_f32 v[4:5], v[62:63], v[4:5]
	v_pk_mul_f32 v[12:13], v[12:13], v[88:89]
	v_add_f32_e32 v4, v4, v5
	v_sub_f32_e32 v30, v30, v31
	v_mul_f32_e32 v31, 0x3e38aa3b, v4
	v_pk_mul_f32 v[4:5], v[108:109], v[12:13]
	v_pk_mul_f32 v[28:29], v[28:29], v[104:105] op_sel_hi:[1,0]
	v_sub_f32_e32 v4, v4, v5
	v_mul_f32_e32 v44, 0x3e38aa3b, v4
	v_pk_mul_f32 v[4:5], v[124:125], v[12:13]
	v_pk_mul_f32 v[28:29], v[28:29], v[154:155]
	v_add_f32_e32 v4, v4, v5
	v_mul_f32_e32 v12, 0x3e38aa3b, v4
	v_pk_mul_f32 v[4:5], v[64:65], v[28:29]
	v_pk_mul_f32 v[52:53], v[52:53], v[104:105] op_sel_hi:[1,0]
	v_sub_f32_e32 v4, v4, v5
	v_mul_f32_e32 v13, 0x3e38aa3b, v4
	v_pk_mul_f32 v[4:5], v[46:47], v[28:29]
	v_lshlrev_b32_e32 v28, 2, v98
	global_load_dword v29, v28, s[14:15]
	v_pk_mul_f32 v[52:53], v[52:53], v[114:115]
	global_load_dword v28, v28, s[16:17]
	v_add_f32_e32 v4, v4, v5
	v_mul_f32_e32 v45, 0x3e38aa3b, v4
	v_pk_mul_f32 v[4:5], v[78:79], v[52:53]
	v_pk_mul_f32 v[6:7], v[6:7], v[104:105] op_sel_hi:[1,0]
	v_sub_f32_e32 v4, v4, v5
	v_mul_f32_e32 v46, 0x3e38aa3b, v4
	v_pk_mul_f32 v[4:5], v[74:75], v[52:53]
	v_pk_mul_f32 v[6:7], v[6:7], v[158:159]
	v_add_f32_e32 v4, v4, v5
	v_mul_f32_e32 v47, 0x3e38aa3b, v4
	v_pk_mul_f32 v[4:5], v[32:33], v[6:7]
	v_pk_mul_f32 v[14:15], v[14:15], v[104:105] op_sel_hi:[1,0]
	v_sub_f32_e32 v4, v4, v5
	v_mul_f32_e32 v32, 0x3e38aa3b, v4
	v_pk_mul_f32 v[4:5], v[16:17], v[6:7]
	v_pk_mul_f32 v[14:15], v[14:15], v[116:117]
	v_add_f32_e32 v4, v4, v5
	v_mul_f32_e32 v6, 0x3e38aa3b, v4
	v_pk_mul_f32 v[4:5], v[72:73], v[14:15]
	v_pk_mul_f32 v[22:23], v[22:23], v[104:105] op_sel_hi:[1,0]
	v_sub_f32_e32 v4, v4, v5
	v_mul_f32_e32 v7, 0x3e38aa3b, v4
	v_pk_mul_f32 v[4:5], v[76:77], v[14:15]
	v_pk_mul_f32 v[22:23], v[22:23], v[150:151]
	v_add_f32_e32 v4, v4, v5
	v_mul_f32_e32 v14, 0x3e38aa3b, v4
	v_pk_mul_f32 v[4:5], v[18:19], v[22:23]
	v_pk_mul_f32 v[50:51], v[50:51], v[104:105] op_sel_hi:[1,0]
	v_sub_f32_e32 v4, v4, v5
	v_mul_f32_e32 v15, 0x3e38aa3b, v4
	v_pk_mul_f32 v[4:5], v[34:35], v[22:23]
	v_pk_mul_f32 v[50:51], v[50:51], v[112:113]
	v_add_f32_e32 v4, v4, v5
	v_mul_f32_e32 v16, 0x3e38aa3b, v4
	v_pk_mul_f32 v[4:5], v[86:87], v[50:51]
	v_pk_mul_f32 v[0:1], v[0:1], v[104:105] op_sel_hi:[1,0]
	v_sub_f32_e32 v4, v4, v5
	v_mul_f32_e32 v17, 0x3e38aa3b, v4
	v_pk_mul_f32 v[4:5], v[70:71], v[50:51]
	v_pk_mul_f32 v[0:1], v[0:1], v[102:103]
	v_add_f32_e32 v4, v4, v5
	v_pk_mul_f32 v[8:9], v[8:9], v[104:105] op_sel_hi:[1,0]
	v_mul_f32_e32 v18, 0x3e38aa3b, v4
	v_pk_mul_f32 v[4:5], v[36:37], v[0:1]
	v_pk_mul_f32 v[0:1], v[20:21], v[0:1]
	v_pk_mul_f32 v[8:9], v[8:9], v[90:91]
	v_add_f32_e32 v0, v0, v1
	v_sub_f32_e32 v4, v4, v5
	v_mul_f32_e32 v5, 0x3e38aa3b, v0
	v_pk_mul_f32 v[0:1], v[68:69], v[8:9]
	v_pk_mul_f32 v[58:59], v[58:59], v[104:105] op_sel_hi:[1,0]
	v_sub_f32_e32 v0, v0, v1
	v_mul_f32_e32 v19, 0x3e38aa3b, v0
	v_pk_mul_f32 v[0:1], v[92:93], v[8:9]
	v_pk_mul_f32 v[58:59], v[58:59], v[126:127]
	v_add_f32_e32 v0, v0, v1
	v_mul_f32_e32 v8, 0x3e38aa3b, v0
	v_pk_mul_f32 v[0:1], v[24:25], v[58:59]
	v_pk_mul_f32 v[48:49], v[48:49], v[104:105] op_sel_hi:[1,0]
	v_sub_f32_e32 v0, v0, v1
	v_mul_f32_e32 v9, 0x3e38aa3b, v0
	v_pk_mul_f32 v[0:1], v[38:39], v[58:59]
	v_pk_mul_f32 v[48:49], v[48:49], v[82:83]
	v_add_f32_e32 v0, v0, v1
	v_mul_f32_e32 v20, 0x3e38aa3b, v0
	v_pk_mul_f32 v[0:1], v[94:95], v[48:49]
	v_pk_mul_f32 v[2:3], v[2:3], v[104:105] op_sel_hi:[1,0]
	v_sub_f32_e32 v0, v0, v1
	v_mul_f32_e32 v21, 0x3e38aa3b, v0
	v_pk_mul_f32 v[0:1], v[66:67], v[48:49]
	v_pk_mul_f32 v[2:3], v[2:3], v[146:147]
	v_add_f32_e32 v0, v0, v1
	v_mul_f32_e32 v22, 0x3e38aa3b, v0
	v_pk_mul_f32 v[0:1], v[40:41], v[2:3]
	v_pk_mul_f32 v[10:11], v[10:11], v[104:105] op_sel_hi:[1,0]
	v_sub_f32_e32 v0, v0, v1
	v_mul_f32_e32 v23, 0x3e38aa3b, v0
	v_pk_mul_f32 v[0:1], v[26:27], v[2:3]
	global_load_dword v2, v199, s[0:1]
	v_pk_mul_f32 v[10:11], v[10:11], v[84:85]
	v_add_f32_e32 v0, v0, v1
	v_mul_f32_e32 v3, 0x3e38aa3b, v0
	v_pk_mul_f32 v[0:1], v[56:57], v[10:11]
	v_cmp_lt_i32_e32 vcc, v215, v209
	v_sub_f32_e32 v0, v0, v1
	v_mul_f32_e32 v24, 0x3e38aa3b, v0
	v_mov_b32_e32 v0, v57
	v_mov_b32_e32 v1, v56
	v_pk_mul_f32 v[0:1], v[0:1], v[10:11]
	v_mul_f32_e32 v4, 0x3e38aa3b, v4
	v_add_f32_e32 v0, v0, v1
	v_cndmask_b32_e32 v1, v207, v215, vcc
	v_mul_f32_e32 v10, 0x3e38aa3b, v0
	s_waitcnt vmcnt(2)
	v_and_b32_e32 v0, 0x7fffffff, v29
	v_lshlrev_b32_e32 v223, 2, v1
	ds_bpermute_b32 v0, v223, v0
	s_waitcnt vmcnt(1)
	v_and_b32_e32 v1, 0x7fffffff, v28
	ds_bpermute_b32 v1, v223, v1
	v_cmp_lt_i32_e32 vcc, v216, v209
	v_cvt_pk_bf16_f32 v146, v15, v4
	v_cvt_pk_bf16_f32 v147, v9, v23
	s_waitcnt lgkmcnt(1)
	v_max_f32_e32 v0, v0, v0
	v_max_f32_e64 v4, |v29|, |v29|
	v_cndmask_b32_e32 v9, v207, v216, vcc
	v_max_f32_e32 v0, v4, v0
	v_lshlrev_b32_e32 v224, 2, v9
	s_waitcnt lgkmcnt(0)
	v_max_f32_e32 v1, v1, v1
	v_max_f32_e64 v4, |v28|, |v28|
	ds_bpermute_b32 v9, v224, v0
	v_max_f32_e32 v1, v4, v1
	ds_bpermute_b32 v4, v224, v1
	v_cvt_pk_bf16_f32 v150, v16, v5
	v_cmp_lt_i32_e32 vcc, v217, v209
	s_waitcnt lgkmcnt(1)
	v_max_f32_e32 v5, v9, v9
	v_max_f32_e32 v0, v0, v5
	v_cndmask_b32_e32 v5, v207, v217, vcc
	s_waitcnt lgkmcnt(0)
	v_max_f32_e32 v4, v4, v4
	v_lshlrev_b32_e32 v5, 2, v5
	v_cvt_pk_bf16_f32 v149, v45, v6
	ds_bpermute_b32 v6, v5, v0
	v_max_f32_e32 v1, v1, v4
	ds_bpermute_b32 v4, v5, v1
	v_cvt_pk_bf16_f32 v151, v20, v3
	v_cmp_lt_i32_e32 vcc, v218, v209
	s_waitcnt lgkmcnt(1)
	v_max_f32_e32 v3, v6, v6
	v_max_f32_e32 v0, v0, v3
	s_waitcnt lgkmcnt(0)
	v_max_f32_e32 v3, v4, v4
	v_cndmask_b32_e32 v4, v207, v218, vcc
	v_lshlrev_b32_e32 v4, 2, v4
	ds_bpermute_b32 v5, v4, v0
	v_max_f32_e32 v1, v1, v3
	ds_bpermute_b32 v3, v4, v1
	v_cmp_lt_i32_e32 vcc, v219, v209
	s_mov_b32 s0, 0x3fb8aa3b
	s_waitcnt lgkmcnt(1)
	v_max_f32_e32 v4, v5, v5
	v_max_f32_e32 v0, v0, v4
	v_cndmask_b32_e32 v4, v207, v219, vcc
	s_waitcnt lgkmcnt(0)
	v_max_f32_e32 v3, v3, v3
	v_lshlrev_b32_e32 v4, 2, v4
	ds_bpermute_b32 v5, v4, v0
	v_max_f32_e32 v1, v1, v3
	ds_bpermute_b32 v3, v4, v1
	v_ashrrev_i32_e32 v200, 2, v96
	v_ashrrev_i32_e32 v201, 31, v200
	s_waitcnt lgkmcnt(1)
	v_max_f32_e32 v4, v5, v5
	v_max_f32_e32 v0, v0, v4
	s_waitcnt lgkmcnt(0)
	v_max_f32_e32 v3, v3, v3
	ds_bpermute_b32 v4, v221, v0
	v_max_f32_e32 v1, v1, v3
	ds_bpermute_b32 v3, v221, v1
	v_bfe_u32 v225, v96, 1, 1
	v_and_b32_e32 v226, 1, v96
	s_waitcnt lgkmcnt(1)
	v_max_f32_e32 v4, v4, v4
	v_max_f32_e32 v0, v0, v4
	s_waitcnt lgkmcnt(0)
	v_max_f32_e32 v3, v3, v3
	v_max_f32_e32 v1, v1, v3
	v_mul_f32_e32 v0, 0x41000000, v0
	v_mul_f32_e32 v0, v1, v0
	v_mul_f32_e32 v0, 0x3fb8aa3b, v0
	s_waitcnt vmcnt(0)
	v_mul_f32_e32 v235, 0x3fb8aa3b, v2
	v_fmamk_f32 v0, v0, 0x3f828f5c, v212
	v_max_f32_e32 v4, v0, v235
	v_fma_f32 v5, v2, s0, -v4
	s_add_u32 s0, s52, 0x10000
	s_addc_u32 s1, s53, 0
	v_lshl_add_u64 v[0:1], s[0:1], 0, v[200:201]
	v_mov_b64_e32 v[2:3], s[28:29]
	v_mad_u64_u32 v[2:3], s[0:1], v0, s25, v[2:3]
	v_mad_i32_i24 v3, v1, s25, v3
	s_lshl_b32 s8, s2, 7
	v_lshl_add_u64 v[0:1], v[2:3], 0, s[8:9]
	v_lshlrev_b32_e32 v198, 6, v225
	v_and_b32_e32 v6, 3, v96
	v_lshl_add_u64 v[2:3], v[0:1], 0, v[198:199]
	v_lshlrev_b32_e32 v198, 4, v226
	v_lshl_add_u64 v[2:3], v[2:3], 0, v[198:199]
	v_lshlrev_b32_e32 v198, 5, v6
	v_lshl_add_u64 v[0:1], v[0:1], 0, v[198:199]
	v_mov_b64_e32 v[88:89], v[176:177]
	v_mov_b64_e32 v[90:91], v[178:179]
	v_mov_b64_e32 v[92:93], v[180:181]
	v_mov_b64_e32 v[94:95], v[182:183]
	v_mov_b64_e32 v[80:81], v[184:185]
	v_mov_b64_e32 v[82:83], v[186:187]
	v_mov_b64_e32 v[84:85], v[188:189]
	v_mov_b64_e32 v[86:87], v[190:191]
	v_exp_f32_e32 v0, v5
	v_cmp_gt_f32_e32 vcc, s31, v4
	v_cmp_gt_u32_e64 s[0:1], 32, v98
	s_ashr_i32 s5, s4, 31
	v_cndmask_b32_e32 v0, 1.0, v0, vcc
	s_lshl_b32 s85, s7, 1
	v_cndmask_b32_e64 v227, 0, v0, s[0:1]
	s_add_i32 s84, s72, -2
	s_lshl_b64 s[0:1], s[4:5], 12
	s_or_b32 s86, s85, 1
	v_lshlrev_b32_e32 v1, 4, v96
	v_lshl_add_u32 v0, v225, 13, 0
	s_add_u32 s52, s52, 0x10080
	v_and_b32_e32 v1, 0xc0, v1
	v_lshlrev_b32_e32 v2, 1, v96
	v_sub_f32_e32 v60, v60, v61
	v_mul_f32_e32 v30, 0x3e38aa3b, v30
	v_cvt_pk_bf16_f32 v154, v17, v19
	v_cvt_pk_bf16_f32 v155, v21, v24
	v_cvt_pk_bf16_f32 v157, v47, v14
	v_cvt_pk_bf16_f32 v158, v18, v8
	v_cvt_pk_bf16_f32 v159, v22, v10
	v_lshlrev_b32_e32 v16, 5, v225
	v_lshlrev_b32_e32 v18, 3, v226
	v_lshlrev_b32_e32 v20, 4, v6
	v_lshl_add_u32 v17, v226, 11, v0
	v_lshlrev_b32_e32 v19, 4, v200
	v_lshl_add_u32 v21, v200, 6, v0
	v_lshlrev_b32_e32 v22, 5, v226
	v_lshlrev_b32_e32 v0, 4, v222
	s_addc_u32 s53, s53, 0
	v_lshl_or_b32 v1, v97, 8, v1
	v_and_b32_e32 v2, 32, v2
	v_lshlrev_b32_e32 v3, 3, v6
	v_mov_b32_e32 v14, v199
	v_mov_b32_e32 v15, v199
	v_mul_f32_e32 v60, 0x3e38aa3b, v60
	v_cvt_pk_bf16_f32 v144, v60, v30
	v_cvt_pk_bf16_f32 v145, v13, v32
	v_cvt_pk_bf16_f32 v148, v42, v31
	v_cvt_pk_bf16_f32 v152, v43, v44
	v_cvt_pk_bf16_f32 v153, v46, v7
	v_cvt_pk_bf16_f32 v156, v54, v12
	v_cmp_ngt_f32_e64 s[2:3], s31, v4
	v_cndmask_b32_e64 v48, 0, -v4, vcc
	v_cmp_gt_u32_e64 s[4:5], 2, v6
	v_or_b32_e32 v229, s6, v222
	s_add_u32 s54, s28, s8
	v_or3_b32 v231, v1, v2, v3
	v_lshl_or_b32 v232, v97, 11, v0
	v_mov_b32_e32 v0, v199
	v_mov_b32_e32 v1, v199
	v_mov_b32_e32 v2, v199
	v_mov_b32_e32 v3, v199
	v_mov_b32_e32 v4, v199
	v_mov_b32_e32 v5, v199
	v_mov_b32_e32 v6, v199
	v_mov_b32_e32 v7, v199
	v_mov_b32_e32 v8, v199
	v_mov_b32_e32 v9, v199
	v_mov_b32_e32 v10, v199
	v_mov_b32_e32 v11, v199
	v_mov_b32_e32 v12, v199
	v_mov_b32_e32 v13, v199
	v_lshlrev_b32_e32 v198, 1, v16
	v_lshlrev_b32_e32 v202, 1, v18
	v_lshlrev_b32_e32 v204, 1, v20
	v_add_u32_e32 v233, v17, v19
	v_add_u32_e32 v234, v21, v22
	v_mov_b64_e32 v[30:31], v[14:15]
	v_mov_b64_e32 v[46:47], v[14:15]
	v_mov_b64_e32 v[78:79], v[14:15]
	s_mov_b32 s73, 0
	v_lshlrev_b32_e32 v228, 2, v97
	v_mov_b32_e32 v49, v48
	v_mov_b32_e32 v50, v48
	v_mov_b32_e32 v51, v48
	v_mov_b32_e32 v52, v48
	v_mov_b32_e32 v53, v48
	v_mov_b32_e32 v54, v48
	v_mov_b32_e32 v55, v48
	v_mov_b32_e32 v56, v48
	v_mov_b32_e32 v57, v48
	v_mov_b32_e32 v58, v48
	v_mov_b32_e32 v59, v48
	v_mov_b32_e32 v60, v48
	v_mov_b32_e32 v61, v48
	v_mov_b32_e32 v62, v48
	v_mov_b32_e32 v63, v48
	v_or_b32_e32 v230, 32, v229
	s_addc_u32 s55, s29, 0
	v_mov_b32_e32 v113, v235
	v_mov_b32_e32 v112, v227
	v_mov_b64_e32 v[28:29], v[12:13]
	v_mov_b64_e32 v[26:27], v[10:11]
	v_mov_b64_e32 v[24:25], v[8:9]
	v_mov_b64_e32 v[22:23], v[6:7]
	v_mov_b64_e32 v[20:21], v[4:5]
	v_mov_b64_e32 v[18:19], v[2:3]
	v_mov_b64_e32 v[16:17], v[0:1]
	v_mov_b64_e32 v[44:45], v[12:13]
	v_mov_b64_e32 v[42:43], v[10:11]
	v_mov_b64_e32 v[40:41], v[8:9]
	v_mov_b64_e32 v[38:39], v[6:7]
	v_mov_b64_e32 v[36:37], v[4:5]
	v_mov_b64_e32 v[34:35], v[2:3]
	v_mov_b64_e32 v[32:33], v[0:1]
	v_mov_b64_e32 v[76:77], v[12:13]
	v_mov_b64_e32 v[74:75], v[10:11]
	v_mov_b64_e32 v[72:73], v[8:9]
	v_mov_b64_e32 v[70:71], v[6:7]
	v_mov_b64_e32 v[68:69], v[4:5]
	v_mov_b64_e32 v[66:67], v[2:3]
	v_mov_b64_e32 v[64:65], v[0:1]
	s_mov_b64 s[6:7], -1
	s_cmp_lt_u32 s73, 2
	s_mov_b32 s8, 0
	s_cbranch_scc1 .LBB0_408
